# v064 + spin-wait loops without s_sleep (grid barrier, stream-K flags, sample-chain wait poll back-to-back); same numerics as baseline
# speedup vs baseline: 1.0051x; 1.0006x over previous
.LBB0_35:
	s_nop 0
	global_load_dword v2, v0, s[12:13] offset:32 sc1
	s_waitcnt vmcnt(0)
	v_and_b32_e32 v2, 0xffff0000, v2
	v_cmp_ne_u32_e32 vcc, v2, v1
	s_or_b64 s[6:7], vcc, s[6:7]
	s_andn2_b64 exec, exec, s[6:7]
	s_cbranch_execnz .LBB0_35

.LBB0_42:
	global_load_dword v15, v16, s[8:9] sc1
	s_waitcnt lgkmcnt(0)
	global_load_dword v0, v16, s[10:11] sc1
	global_load_dword v1, v16, s[12:13] sc1
	global_load_dword v2, v16, s[14:15] sc1
	global_load_dword v3, v16, s[16:17] sc1
	global_load_dword v4, v16, s[18:19] sc1
	global_load_dword v5, v16, s[20:21] sc1
	global_load_dword v6, v16, s[22:23] sc1
	global_load_dword v7, v16, s[24:25] sc1
	global_load_dword v8, v16, s[26:27] sc1
	global_load_dword v9, v16, s[28:29] sc1
	global_load_dword v10, v16, s[30:31] sc1
	global_load_dword v11, v16, s[34:35] sc1
	global_load_dword v12, v16, s[36:37] sc1
	global_load_dword v13, v16, s[38:39] sc1
	global_load_dword v14, v16, s[40:41] sc1
	s_mov_b64 s[42:43], -1
	s_mov_b64 s[44:45], -1
	s_waitcnt vmcnt(14)
	v_add_u32_e32 v17, v0, v15
	s_waitcnt vmcnt(13)
	v_add_u32_e32 v17, v17, v1
	s_waitcnt vmcnt(12)
	v_add_u32_e32 v17, v17, v2
	s_waitcnt vmcnt(11)
	v_add_u32_e32 v17, v17, v3
	s_waitcnt vmcnt(10)
	v_add_u32_e32 v17, v17, v4
	s_waitcnt vmcnt(9)
	v_add_u32_e32 v17, v17, v5
	s_waitcnt vmcnt(8)
	v_add_u32_e32 v17, v17, v6
	s_waitcnt vmcnt(7)
	v_add_u32_e32 v17, v17, v7
	s_waitcnt vmcnt(6)
	v_add_u32_e32 v17, v17, v8
	s_waitcnt vmcnt(5)
	v_add_u32_e32 v17, v17, v9
	s_waitcnt vmcnt(4)
	v_add_u32_e32 v17, v17, v10
	s_waitcnt vmcnt(3)
	v_add_u32_e32 v17, v17, v11
	s_waitcnt vmcnt(2)
	v_add_u32_e32 v17, v17, v12
	s_waitcnt vmcnt(1)
	v_add_u32_e32 v17, v17, v13
	s_waitcnt vmcnt(0)
	v_add_u32_e32 v17, v17, v14
	v_cmp_eq_u32_e32 vcc, s48, v17
	s_cbranch_vccnz .LBB0_41
	s_and_b32 s42, s49, 0xff
	s_cmp_eq_u32 s42, 0
	s_mov_b64 s[42:43], -1
	s_mov_b64 s[46:47], -1
	s_nop 0
	s_cbranch_scc1 .LBB0_46
	s_and_b64 vcc, exec, s[46:47]
	s_cbranch_vccz .LBB0_41

.LBB0_60:
	s_and_b32 s22, s3, 0xff
	s_mov_b64 s[20:21], -1
	s_cmp_lg_u32 s22, 0
	s_mov_b64 s[24:25], -1
	s_nop 0
	s_cbranch_scc0 .LBB0_63
	s_and_b64 vcc, exec, s[24:25]
	s_cbranch_vccz .LBB0_59

.LBB0_77:
	s_and_b32 s18, s3, 0xff
	s_cmp_lg_u32 s18, 0
	s_mov_b64 s[20:21], -1
	s_nop 0
	s_cbranch_scc0 .LBB0_80
	s_mov_b64 s[22:23], -1
	s_and_b64 vcc, exec, s[20:21]
	s_cbranch_vccz .LBB0_76

.LBB0_586:
	global_load_dword v15, v185, s[12:13] sc1
	s_waitcnt lgkmcnt(0)
	global_load_dword v0, v185, s[14:15] sc1
	global_load_dword v1, v185, s[16:17] sc1
	global_load_dword v2, v185, s[18:19] sc1
	global_load_dword v3, v185, s[20:21] sc1
	global_load_dword v4, v185, s[22:23] sc1
	global_load_dword v5, v185, s[24:25] sc1
	global_load_dword v6, v185, s[26:27] sc1
	global_load_dword v7, v185, s[28:29] sc1
	global_load_dword v8, v185, s[30:31] sc1
	global_load_dword v9, v185, s[34:35] sc1
	global_load_dword v10, v185, s[36:37] sc1
	global_load_dword v11, v185, s[38:39] sc1
	global_load_dword v12, v185, s[40:41] sc1
	global_load_dword v13, v185, s[42:43] sc1
	global_load_dword v14, v185, s[44:45] sc1
	s_mov_b64 s[46:47], -1
	s_mov_b64 s[48:49], -1
	s_waitcnt vmcnt(14)
	v_add_u32_e32 v16, v0, v15
	s_waitcnt vmcnt(13)
	v_add_u32_e32 v16, v16, v1
	s_waitcnt vmcnt(12)
	v_add_u32_e32 v16, v16, v2
	s_waitcnt vmcnt(11)
	v_add_u32_e32 v16, v16, v3
	s_waitcnt vmcnt(10)
	v_add_u32_e32 v16, v16, v4
	s_waitcnt vmcnt(9)
	v_add_u32_e32 v16, v16, v5
	s_waitcnt vmcnt(8)
	v_add_u32_e32 v16, v16, v6
	s_waitcnt vmcnt(7)
	v_add_u32_e32 v16, v16, v7
	s_waitcnt vmcnt(6)
	v_add_u32_e32 v16, v16, v8
	s_waitcnt vmcnt(5)
	v_add_u32_e32 v16, v16, v9
	s_waitcnt vmcnt(4)
	v_add_u32_e32 v16, v16, v10
	s_waitcnt vmcnt(3)
	v_add_u32_e32 v16, v16, v11
	s_waitcnt vmcnt(2)
	v_add_u32_e32 v16, v16, v12
	s_waitcnt vmcnt(1)
	v_add_u32_e32 v16, v16, v13
	s_waitcnt vmcnt(0)
	v_add_u32_e32 v16, v16, v14
	v_cmp_eq_u32_e32 vcc, s95, v16
	s_cbranch_vccnz .LBB0_585
	s_and_b32 s3, s1, 0xff
	s_cmp_eq_u32 s3, 0
	s_mov_b64 s[50:51], -1
	s_nop 0
	s_cbranch_scc1 .LBB0_590
	s_and_b64 vcc, exec, s[50:51]
	s_cbranch_vccz .LBB0_584

.LBB0_604:
	s_and_b32 s1, s0, 0xff
	s_mov_b64 s[24:25], -1
	s_cmp_lg_u32 s1, 0
	s_mov_b64 s[28:29], -1
	s_nop 0
	s_cbranch_scc0 .LBB0_607
	s_and_b64 vcc, exec, s[28:29]
	s_cbranch_vccz .LBB0_603

.LBB0_621:
	s_and_b32 s1, s0, 0xff
	s_mov_b64 s[22:23], -1
	s_cmp_lg_u32 s1, 0
	s_mov_b64 s[26:27], -1
	s_nop 0
	s_cbranch_scc0 .LBB0_624
	s_and_b64 vcc, exec, s[26:27]
	s_cbranch_vccz .LBB0_620

.LBB0_1261:
	global_load_dword v15, v185, s[16:17] sc1
	s_waitcnt lgkmcnt(0)
	global_load_dword v0, v185, s[18:19] sc1
	global_load_dword v1, v185, s[20:21] sc1
	global_load_dword v2, v185, s[22:23] sc1
	global_load_dword v3, v185, s[24:25] sc1
	global_load_dword v4, v185, s[26:27] sc1
	global_load_dword v5, v185, s[28:29] sc1
	global_load_dword v6, v185, s[30:31] sc1
	global_load_dword v7, v185, s[34:35] sc1
	global_load_dword v8, v185, s[36:37] sc1
	global_load_dword v9, v185, s[38:39] sc1
	global_load_dword v10, v185, s[40:41] sc1
	global_load_dword v11, v185, s[42:43] sc1
	global_load_dword v12, v185, s[44:45] sc1
	global_load_dword v13, v185, s[46:47] sc1
	global_load_dword v14, v185, s[48:49] sc1
	s_mov_b64 s[50:51], -1
	s_mov_b64 s[52:53], -1
	s_waitcnt vmcnt(14)
	v_add_u32_e32 v16, v0, v15
	s_waitcnt vmcnt(13)
	v_add_u32_e32 v16, v16, v1
	s_waitcnt vmcnt(12)
	v_add_u32_e32 v16, v16, v2
	s_waitcnt vmcnt(11)
	v_add_u32_e32 v16, v16, v3
	s_waitcnt vmcnt(10)
	v_add_u32_e32 v16, v16, v4
	s_waitcnt vmcnt(9)
	v_add_u32_e32 v16, v16, v5
	s_waitcnt vmcnt(8)
	v_add_u32_e32 v16, v16, v6
	s_waitcnt vmcnt(7)
	v_add_u32_e32 v16, v16, v7
	s_waitcnt vmcnt(6)
	v_add_u32_e32 v16, v16, v8
	s_waitcnt vmcnt(5)
	v_add_u32_e32 v16, v16, v9
	s_waitcnt vmcnt(4)
	v_add_u32_e32 v16, v16, v10
	s_waitcnt vmcnt(3)
	v_add_u32_e32 v16, v16, v11
	s_waitcnt vmcnt(2)
	v_add_u32_e32 v16, v16, v12
	s_waitcnt vmcnt(1)
	v_add_u32_e32 v16, v16, v13
	s_waitcnt vmcnt(0)
	v_add_u32_e32 v16, v16, v14
	v_cmp_eq_u32_e32 vcc, s95, v16
	s_cbranch_vccnz .LBB0_1260
	s_and_b32 s3, s1, 0xff
	s_cmp_eq_u32 s3, 0
	s_mov_b64 s[54:55], -1
	s_nop 0
	s_cbranch_scc1 .LBB0_1265
	s_and_b64 vcc, exec, s[54:55]
	s_cbranch_vccz .LBB0_1260

.LBB0_1279:
	s_and_b32 s1, s0, 0xff
	s_mov_b64 s[28:29], -1
	s_cmp_lg_u32 s1, 0
	s_mov_b64 s[34:35], -1
	s_nop 0
	s_cbranch_scc0 .LBB0_1282
	s_and_b64 vcc, exec, s[34:35]
	s_cbranch_vccz .LBB0_1278

.LBB0_1296:
	s_and_b32 s1, s0, 0xff
	s_mov_b64 s[26:27], -1
	s_cmp_lg_u32 s1, 0
	s_mov_b64 s[30:31], -1
	s_nop 0
	s_cbranch_scc0 .LBB0_1299
	s_and_b64 vcc, exec, s[30:31]
	s_cbranch_vccz .LBB0_1295

.LBB0_1376:
	global_load_dword v0, v185, s[6:7] sc1
	s_mov_b64 s[10:11], -1
	s_waitcnt vmcnt(0)
	v_cmp_lt_u32_e32 vcc, 15, v0
	s_cbranch_vccnz .LBB0_1375
	s_nop 0
	global_load_dword v0, v185, s[6:7] sc1
	s_waitcnt vmcnt(0)
	v_cmp_gt_u32_e32 vcc, 16, v0
	s_cbranch_vccz .LBB0_1375
	s_nop 0
	global_load_dword v0, v185, s[6:7] sc1
	s_waitcnt vmcnt(0)
	v_cmp_gt_u32_e32 vcc, 16, v0
	s_cbranch_vccz .LBB0_1375
	s_nop 0
	global_load_dword v0, v185, s[6:7] sc1
	s_waitcnt vmcnt(0)
	v_cmp_gt_u32_e32 vcc, 16, v0
	s_cbranch_vccz .LBB0_1375
	s_nop 0
	global_load_dword v0, v185, s[6:7] sc1
	s_waitcnt vmcnt(0)
	v_cmp_gt_u32_e32 vcc, 16, v0
	s_cbranch_vccz .LBB0_1375
	s_add_i32 s0, s0, -5
	s_cmp_eq_u32 s0, 0
	s_cselect_b64 s[10:11], -1, 0
	s_nop 0
	s_branch .LBB0_1375

.LBB0_1404:
	global_load_dword v128, v185, s[80:81] sc1
	s_mov_b64 s[82:83], -1
	s_waitcnt vmcnt(0)
	v_cmp_lt_u32_e32 vcc, 7, v128
	s_cbranch_vccnz .LBB0_1403
	s_nop 0
	global_load_dword v128, v185, s[80:81] sc1
	s_waitcnt vmcnt(0)
	v_cmp_gt_u32_e32 vcc, 8, v128
	s_cbranch_vccz .LBB0_1403
	s_nop 0
	global_load_dword v128, v185, s[80:81] sc1
	s_waitcnt vmcnt(0)
	v_cmp_gt_u32_e32 vcc, 8, v128
	s_cbranch_vccz .LBB0_1403
	s_nop 0
	global_load_dword v128, v185, s[80:81] sc1
	s_waitcnt vmcnt(0)
	v_cmp_gt_u32_e32 vcc, 8, v128
	s_cbranch_vccz .LBB0_1403
	s_nop 0
	global_load_dword v128, v185, s[80:81] sc1
	s_waitcnt vmcnt(0)
	v_cmp_gt_u32_e32 vcc, 8, v128
	s_cbranch_vccz .LBB0_1403
	s_add_i32 s35, s35, -5
	s_cmp_eq_u32 s35, 0
	s_cselect_b64 s[82:83], -1, 0
	s_nop 0
	s_branch .LBB0_1403
